# kernel-start READY wait and census post moved into the first grid barrier (P0 starts immediately)
# baseline (speedup 1.0000x reference)
; #define LAS __attribute__((address_space(3)))
; __device__ __forceinline__ bool p0_decode(int it, const P0Src& t, int wid, int lane, P0Desc& d) {
;     if (it >= 2 * P0_I_L) return false;
;     const int l = it / P0_I_L; int rr = it - l * P0_I_L; const float* W; int ldw, nv, K, blk, kb, dg; bf16_t* WT; bool perm; const float* gk = nullptr;
;     if (rr < P0_I_IN) { blk = rr >> 5; kb = rr & 31; const int sg = blk * 8 + wid; W = t.w_in + (size_t)l * DM * INC; ldw = INC; nv = INC; K = DM; WT = t.WT_IN + (size_t)l * INP * DM; gk = t.g_mix + (size_t)l * DM;
;         if (sg < 32) { dg = 64 + sg; perm = true; } else if (sg < 64) { const int q = sg - 32; dg = (q >> 2) * 8 + (q & 3); perm = true; } else if (sg < 96) { const int q = sg - 64; dg = (q >> 2) * 8 + 4 + (q & 3); perm = true; }
;         else { dg = sg; perm = sg < 192; } }
;     else if ((rr -= P0_I_IN) < P0_I_OUT) { blk = rr >> 5; kb = rr & 31; dg = blk * 8 + wid; perm = true; W = t.w_out + (size_t)l * DM * DM; ldw = DM; nv = DM; K = DM; WT = t.WT_OUT + (size_t)l * DM * DM; }
;     else if ((rr -= P0_I_OUT) < P0_I_UP) { blk = rr >> 5; kb = rr & 31; const int sg = blk * 8 + wid; perm = true; W = t.w_up + (size_t)l * DM * UPN; ldw = UPN; nv = UPN; K = DM; WT = t.WT_UP + (size_t)l * UPN * DM; gk = t.g_ffn + (size_t)l * DM;
;         if (sg < 176) dg = (sg >> 2) * 8 + (sg & 3); else { const int q = sg - 176; dg = (q >> 2) * 8 + 4 + (q & 3); } }
; __global__ void __launch_bounds__(NTHR, 2) fwd_kernel(Args a) {
;     ...
;     { unsigned* bw = (unsigned*)(a.ws + WS_BAR); unsigned* rdy = bw + 4000;
;       if (blockIdx.x == 0) { for (int i = threadIdx.x; i < XCD_BAR_WORDS; i += NTHR) __hip_atomic_store(bw + i, 0u, __ATOMIC_RELAXED, __HIP_MEMORY_SCOPE_AGENT);
;           asm volatile("s_waitcnt vmcnt(0)" ::: "memory"); __syncthreads();
;           if (threadIdx.x == 0) { __builtin_amdgcn_fence(__ATOMIC_RELEASE, "agent"); __hip_atomic_store(rdy, 0x5EEDBA55u, __ATOMIC_RELAXED, __HIP_MEMORY_SCOPE_AGENT); } }
;       if (threadIdx.x == 0) { unsigned spins = 0u;
;           while (__hip_atomic_load(rdy, __ATOMIC_RELAXED, __HIP_MEMORY_SCOPE_AGENT) != 0x5EEDBA55u && ++spins < (1u << 22)) __builtin_amdgcn_s_sleep(2);
;           __builtin_amdgcn_fence(__ATOMIC_ACQUIRE, "agent");
;           ((volatile LAS unsigned*)(lds + LDS_BARST + 16))[0] = xb_add(&bw[XB_XCNT(xb_xcc_id())], 1u); }
;       __syncthreads(); }
.LBB0_20:
	v_cmp_eq_u32_e64 s[4:5], 0, v210
	s_mov_b64 s[2:3], exec
	s_nop 0
	v_writelane_b32 v246, s4, 2
	s_nop 1
	v_writelane_b32 v246, s5, 3
	s_and_b64 s[4:5], s[2:3], s[4:5]
	s_mov_b64 exec, s[4:5]
.LBB0_35:
	s_or_b64 exec, exec, s[2:3]
	s_mov_b64 s[2:3], s[90:91]
	s_waitcnt lgkmcnt(0)
	s_barrier
	v_mov_b32_e32 v33, v210
	s_load_dwordx2 s[4:5], s[2:3], 0x68
	s_load_dwordx2 s[16:17], s[2:3], 0x80
	s_load_dwordx2 s[0:1], s[2:3], 0x98
	s_cmpk_lt_i32 s62, 0x18c0
	v_readfirstlane_b32 s36, v33
	s_cselect_b64 s[22:23], -1, 0
	s_ashr_i32 s33, s36, 6
	s_waitcnt lgkmcnt(0)
	s_add_u32 s44, s0, 0x3200000
	s_load_dwordx4 s[8:11], s[2:3], 0x28
	s_load_dwordx4 s[12:15], s[2:3], 0x58
	s_addc_u32 s45, s1, 0
	s_add_u32 s47, s0, 0x4200000
	s_addc_u32 s48, s1, 0
	s_add_u32 s49, s0, 0x9a00000
	v_and_b32_e32 v32, 63, v33
	s_addc_u32 s50, s1, 0
	s_and_b64 vcc, exec, s[22:23]
	s_cbranch_vccz .LBB0_41
	s_mul_hi_i32 s6, s62, 0xa57eb503
	s_add_i32 s6, s6, s62
	s_lshr_b32 s7, s6, 31
	s_ashr_i32 s6, s6, 11
	s_add_i32 s30, s6, s7
	s_mul_i32 s40, s30, 0xfffff3a0
	s_ashr_i32 s31, s30, 31
	s_add_i32 s40, s40, s62
	s_and_b32 s37, s62, 31
	s_lshl_b64 s[28:29], s[30:31], 13
	s_cmpk_gt_i32 s40, 0x31f
	s_mov_b64 s[18:19], -1
	s_cbranch_scc0 .LBB0_42
	v_mov_b32_e32 v0, 0x420
	v_sub_co_u32_e32 v0, vcc, s40, v0
	s_andn2_b64 vcc, exec, vcc
	v_readfirstlane_b32 s26, v0
	s_cbranch_vccz .LBB0_43
	v_mov_b32_e32 v0, 0x9a0
	v_sub_co_u32_e32 v0, vcc, s40, v0
	s_nop 0
	v_readfirstlane_b32 s6, v0
	s_mul_hi_i32 s27, s30, 0x2c00000
	s_andn2_b64 vcc, exec, vcc
	s_mul_i32 s42, s30, 0x2c00000
	s_cbranch_vccz .LBB0_51
	s_mul_hi_u32 s7, s6, 0xba2e8ba3
	s_lshr_b32 s38, s7, 6
	s_mul_i32 s7, s38, 0xffffffa8
	s_add_i32 s41, s7, s6
	s_lshl_b32 s6, s38, 3
	s_add_i32 s39, s33, s6
	s_add_u32 s20, s16, s42
	s_mul_i32 s24, s30, 0x1600000
	s_addc_u32 s21, s17, s27
	s_mul_hi_i32 s7, s30, 0x1600000
	s_add_u32 s6, s49, s24
	s_addc_u32 s7, s50, s7
	s_mov_b64 s[34:35], 0
	s_cbranch_execz .LBB0_52
	s_movk_i32 s51, 0x1600
	s_movk_i32 s24, 0x800
	s_mov_b64 s[26:27], 0
	s_andn2_b64 vcc, exec, s[34:35]
	s_cbranch_vccz .LBB0_44
	s_branch .LBB0_45

; #define LAS __attribute__((address_space(3)))
; __device__ __forceinline__ unsigned xb_add(unsigned* p, unsigned v) { return __hip_atomic_fetch_add(p, v, __ATOMIC_RELAXED, __HIP_MEMORY_SCOPE_AGENT); }
; __device__ __forceinline__ unsigned xb_xcc_id() { return (unsigned)__builtin_amdgcn_s_getreg((3 << 11) | 20) & 0xFu; }
; __device__ __forceinline__ void xcd_barrier(const XcdBarrier& b) {
;     asm volatile("s_waitcnt vmcnt(0)" ::: "memory");
;     __syncthreads();
;     if (threadIdx.x == 0) {
;         unsigned* bar = b.bar;
;         __builtin_amdgcn_s_waitcnt(0);
;         unsigned nloc = b.st[0], nx = b.st[1];
;         if (nloc == 0u) { xcd_barrier_complete(bar, b.x, nloc, nx); b.st[0] = nloc; b.st[1] = nx; }
; __global__ void __launch_bounds__(NTHR, 2) fwd_kernel(Args a) {
;     ...
;       if (threadIdx.x == 0) { unsigned spins = 0u;
;           while (__hip_atomic_load(rdy, __ATOMIC_RELAXED, __HIP_MEMORY_SCOPE_AGENT) != 0x5EEDBA55u && ++spins < (1u << 22)) __builtin_amdgcn_s_sleep(2);
;           __builtin_amdgcn_fence(__ATOMIC_ACQUIRE, "agent");
;           ((volatile LAS unsigned*)(lds + LDS_BARST + 16))[0] = xb_add(&bw[XB_XCNT(xb_xcc_id())], 1u); }
.LBB0_173:
	s_or_b64 exec, exec, s[2:3]
	s_mov_b64 s[0:1], s[90:91]
	s_load_dwordx2 s[0:1], s[0:1], 0x98
	s_getreg_b32 s2, hwreg(HW_REG_XCC_ID, 0, 4)
	s_waitcnt vmcnt(0)
	s_waitcnt lgkmcnt(0)
	s_barrier
	s_add_u32 s47, s0, 0x221e4000
	s_addc_u32 s48, s1, 0
	s_and_b32 s49, s2, 15
	s_mov_b64 s[2:3], exec
	v_readlane_b32 s4, v246, 2
	v_readlane_b32 s5, v246, 3
	s_and_b64 s[4:5], s[2:3], s[4:5]
	s_mov_b64 exec, s[4:5]
	s_cbranch_execz .LBB0_225
	s_add_u32 s98, s0, 0x221e7e80
	s_addc_u32 s99, s1, 0
	v_mov_b32_e32 v0, 0
	s_mov_b32 s100, 0x400000
.Lrdy_spin:
	global_load_dword v1, v0, s[98:99] sc1
	s_waitcnt vmcnt(0)
	v_cmp_eq_u32_e32 vcc, 0x5eedba55, v1
	s_cbranch_vccnz .Lrdy_ok
	s_sleep 2
	s_add_i32 s100, s100, -1
	s_cmp_eq_u32 s100, 0
	s_cbranch_scc0 .Lrdy_spin
.Lrdy_ok:
	buffer_inv sc1
	s_lshl_b32 s100, s49, 8
	s_add_u32 s98, s47, s100
	s_addc_u32 s99, s48, 0
	v_mov_b32_e32 v1, 1
	global_atomic_add v1, v0, v1, s[98:99] offset:1024 sc0
	s_waitcnt vmcnt(0)
	s_add_i32 s100, 0, 0x23fd0
	v_mov_b32_e32 v0, s100
	ds_write_b32 v0, v1
	s_waitcnt lgkmcnt(0)
	s_add_i32 s4, 0, 0x23fc0
	v_mov_b32_e32 v0, s4
	s_waitcnt vmcnt(0) expcnt(0) lgkmcnt(0)
	ds_read_b32 v2, v0
	s_add_i32 s4, 0, 0x23fc4
	v_mov_b32_e32 v0, s4
	ds_read_b32 v0, v0
	s_waitcnt lgkmcnt(1)
	v_cmp_ne_u32_e32 vcc, 0, v2
	s_cbranch_vccnz .LBB0_189
	s_add_u32 s4, s0, 0x221e4200
	s_addc_u32 s5, s1, 0
	s_add_u32 s6, s0, 0x221e4400
	s_addc_u32 s7, s1, 0
	s_add_u32 s8, s0, 0x221e4500
	s_addc_u32 s9, s1, 0
	s_add_u32 s10, s0, 0x221e4600
	s_addc_u32 s11, s1, 0
	s_add_u32 s12, s0, 0x221e4700
	s_addc_u32 s13, s1, 0
	s_add_u32 s14, s0, 0x221e4800
	s_addc_u32 s15, s1, 0
	s_add_u32 s16, s0, 0x221e4900
	s_addc_u32 s17, s1, 0
	s_add_u32 s18, s0, 0x221e4a00
	s_addc_u32 s19, s1, 0
	s_add_u32 s20, s0, 0x221e4b00
	s_addc_u32 s21, s1, 0
	s_add_u32 s22, s0, 0x221e4c00
	s_addc_u32 s23, s1, 0
	s_add_u32 s24, s0, 0x221e4d00
	s_addc_u32 s25, s1, 0
	s_add_u32 s26, s0, 0x221e4e00
	s_addc_u32 s27, s1, 0
	s_add_u32 s28, s0, 0x221e4f00
	s_addc_u32 s29, s1, 0
	s_add_u32 s30, s0, 0x221e5000
	s_addc_u32 s31, s1, 0
	s_add_u32 s34, s0, 0x221e5100
	s_addc_u32 s35, s1, 0
	s_add_u32 s36, s0, 0x221e5200
	s_addc_u32 s37, s1, 0
	s_mul_i32 s33, s83, s46
	s_add_u32 s38, s0, 0x221e5300
	s_mul_i32 s33, s33, s82
	s_addc_u32 s39, s1, 0
	s_mov_b32 s50, 1
	v_mov_b32_e32 v17, 0
	s_branch .LBB0_177
